# C loop: VALU-free SGPR-base LDS-DMA issued in the first two LDS-wait shadows of each step (plus A DMA restructure and A VALU cleanup)
# speedup vs baseline: 1.0053x; 1.0044x over previous
.LBB0_541:
	s_add_i32 s10, s0, 0xf000
	ds_read_b128 v[96:99], v201 offset:20480
	ds_read_b128 v[144:147], v201 offset:24576
	ds_read_b128 v[100:103], v202 offset:20480
	ds_read_b128 v[168:171], v202 offset:24576
	v_exp_f32_e32 v180, v80
	v_exp_f32_e32 v181, v81
	v_exp_f32_e32 v182, v82
	v_exp_f32_e32 v183, v83
	s_mov_b32 m0, s10
	s_nop 0
	global_load_lds_dwordx4 v244, s[12:13]
	s_waitcnt lgkmcnt(0)
	v_mfma_f32_32x32x16_bf16 v[112:127], v[96:99], v[132:135], v[48:63]
	ds_read_b128 v[80:83], v204 offset:20480
	ds_read_b128 v[174:177], v204 offset:24576
	v_exp_f32_e32 v84, v84
	v_exp_f32_e32 v85, v85
	v_exp_f32_e32 v86, v86
	v_exp_f32_e32 v87, v87
	v_mfma_f32_32x32x16_bf16 v[112:127], v[100:103], v[128:131], v[112:127]
	v_cvt_pk_bf16_f32 v180, v180, v181
	v_cvt_pk_bf16_f32 v181, v182, v183
	v_cvt_pk_bf16_f32 v182, v84, v85
	v_cvt_pk_bf16_f32 v183, v86, v87
	v_mfma_f32_32x32x16_bf16 v[96:111], v[144:147], v[132:135], v[48:63]
	ds_read_b128 v[84:87], v203 offset:20480
	ds_read_b128 v[144:147], v203 offset:24576
	s_mov_b32 m0, s8
	s_nop 0
	global_load_lds_dwordx4 v245, s[14:15]
	s_waitcnt lgkmcnt(0)
	v_mfma_f32_32x32x16_bf16 v[112:127], v[80:83], v[140:143], v[112:127]
	v_exp_f32_e32 v80, v88
	v_exp_f32_e32 v81, v89
	v_exp_f32_e32 v82, v90
	v_exp_f32_e32 v83, v91
	v_mfma_f32_32x32x16_bf16 v[112:127], v[84:87], v[136:139], v[112:127]
	v_exp_f32_e32 v84, v92
	v_exp_f32_e32 v85, v93
	v_exp_f32_e32 v86, v94
	v_exp_f32_e32 v87, v95
	v_mfma_f32_32x32x16_bf16 v[96:111], v[168:171], v[128:131], v[96:111]
	v_cvt_pk_bf16_f32 v168, v80, v81
	v_cvt_pk_bf16_f32 v169, v82, v83
	v_cvt_pk_bf16_f32 v170, v84, v85
	v_cvt_pk_bf16_f32 v171, v86, v87
	ds_read_b128 v[80:83], v206 offset:8192
	ds_read_b128 v[84:87], v206 offset:12288
	v_mfma_f32_32x32x16_bf16 v[96:111], v[174:177], v[140:143], v[96:111]
	s_waitcnt lgkmcnt(0)
	v_mfma_f32_32x32x16_bf16 v[0:15], v[84:87], v[180:183], v[0:15]
	ds_read_b128 v[88:91], v205 offset:8192
	ds_read_b128 v[92:95], v205 offset:12288
	v_exp_f32_e32 v217, v64
	v_exp_f32_e32 v218, v65
	v_exp_f32_e32 v219, v66
	v_exp_f32_e32 v216, v67
	v_exp_f32_e32 v221, v68
	v_exp_f32_e32 v222, v69
	v_mfma_f32_32x32x16_bf16 v[16:31], v[80:83], v[180:183], v[16:31]
	v_exp_f32_e32 v223, v70
	v_exp_f32_e32 v220, v71
	v_cvt_pk_bf16_f32 v64, v217, v218
	v_cvt_pk_bf16_f32 v65, v219, v216
	v_cvt_pk_bf16_f32 v66, v221, v222
	v_cvt_pk_bf16_f32 v67, v223, v220
	s_waitcnt lgkmcnt(0)
	v_mfma_f32_32x32x16_bf16 v[0:15], v[92:95], v[168:171], v[0:15]
	ds_read_b128 v[68:71], v200 offset:8192
	ds_read_b128 v[174:177], v200 offset:12288
	v_exp_f32_e32 v225, v72
	v_exp_f32_e32 v226, v73
	v_exp_f32_e32 v227, v74
	v_exp_f32_e32 v224, v75
	v_exp_f32_e32 v229, v76
	v_exp_f32_e32 v230, v77
	v_mfma_f32_32x32x16_bf16 v[16:31], v[88:91], v[168:171], v[16:31]
	v_exp_f32_e32 v231, v78
	v_exp_f32_e32 v228, v79
	v_cvt_pk_bf16_f32 v72, v225, v226
	v_cvt_pk_bf16_f32 v73, v227, v224
	v_cvt_pk_bf16_f32 v74, v229, v230
	v_cvt_pk_bf16_f32 v75, v231, v228
	v_mfma_f32_32x32x16_bf16 v[96:111], v[144:147], v[136:139], v[96:111]
	s_waitcnt lgkmcnt(0)
	v_mfma_f32_32x32x16_bf16 v[16:31], v[68:71], v[64:67], v[16:31]
	ds_read_b128 v[76:79], v151 offset:8192
	ds_read_b128 v[184:187], v151 offset:12288
	s_waitcnt lgkmcnt(0)
	v_mfma_f32_32x32x16_bf16 v[16:31], v[76:79], v[72:75], v[16:31]
	s_waitcnt vmcnt(2)
	s_mov_b32 m0, s0
	s_waitcnt lgkmcnt(0)
	s_barrier
	ds_read_b128 v[68:71], v201 offset:40960
	ds_read_b128 v[188:191], v201 offset:45056
	v_mfma_f32_32x32x16_bf16 v[0:15], v[174:177], v[64:67], v[0:15]
	v_mov_b64_e32 v[146:147], s[38:39]
	v_mov_b64_e32 v[144:145], s[36:37]
	ds_read_b128 v[64:67], v202 offset:40960
	ds_read_b128 v[174:177], v202 offset:45056
	v_exp_f32_e32 v192, v112
	v_exp_f32_e32 v193, v113
	v_exp_f32_e32 v194, v114
	v_exp_f32_e32 v195, v115
	s_mov_b32 m0, s0
	s_nop 0
	global_load_lds_dwordx4 v244, s[16:17]
	s_waitcnt lgkmcnt(0)
	v_mfma_f32_32x32x16_bf16 v[80:95], v[68:71], v[132:135], v[48:63]
	v_mfma_f32_32x32x16_bf16 v[32:47], v[144:147], v[180:183], v[32:47]
	v_mfma_f32_32x32x16_bf16 v[0:15], v[184:187], v[72:75], v[0:15]
	v_mfma_f32_32x32x16_bf16 v[80:95], v[64:67], v[128:131], v[80:95]
	ds_read_b128 v[112:115], v204 offset:40960
	ds_read_b128 v[180:183], v204 offset:45056
	v_exp_f32_e32 v116, v116
	v_exp_f32_e32 v117, v117
	v_exp_f32_e32 v118, v118
	v_exp_f32_e32 v119, v119
	v_cvt_pk_bf16_f32 v192, v192, v193
	v_cvt_pk_bf16_f32 v193, v194, v195
	v_mfma_f32_32x32x16_bf16 v[64:79], v[188:191], v[132:135], v[48:63]
	v_cvt_pk_bf16_f32 v194, v116, v117
	v_cvt_pk_bf16_f32 v195, v118, v119
	s_mov_b32 m0, s1
	s_nop 0
	global_load_lds_dwordx4 v245, s[18:19]
	s_waitcnt lgkmcnt(0)
	v_mfma_f32_32x32x16_bf16 v[80:95], v[112:115], v[140:143], v[80:95]
	ds_read_b128 v[112:115], v203 offset:40960
	ds_read_b128 v[116:119], v203 offset:45056
	v_exp_f32_e32 v120, v120
	v_exp_f32_e32 v121, v121
	v_exp_f32_e32 v122, v122
	v_exp_f32_e32 v123, v123
	v_mfma_f32_32x32x16_bf16 v[32:47], v[144:147], v[168:171], v[32:47]
	v_mfma_f32_32x32x16_bf16 v[64:79], v[174:177], v[128:131], v[64:79]
	v_cvt_pk_bf16_f32 v174, v120, v121
	v_cvt_pk_bf16_f32 v175, v122, v123
	s_waitcnt lgkmcnt(0)
	v_mfma_f32_32x32x16_bf16 v[80:95], v[112:115], v[136:139], v[80:95]
	v_exp_f32_e32 v112, v124
	v_exp_f32_e32 v113, v125
	v_exp_f32_e32 v114, v126
	v_exp_f32_e32 v115, v127
	v_cvt_pk_bf16_f32 v176, v112, v113
	v_cvt_pk_bf16_f32 v177, v114, v115
	v_mfma_f32_32x32x16_bf16 v[64:79], v[180:183], v[140:143], v[64:79]
	ds_read_b128 v[112:115], v206 offset:28672
	ds_read_b128 v[120:123], v206 offset:32768
	s_waitcnt lgkmcnt(0)
	v_mfma_f32_32x32x16_bf16 v[0:15], v[120:123], v[192:195], v[0:15]
	ds_read_b128 v[124:127], v205 offset:28672
	ds_read_b128 v[180:183], v205 offset:32768
	v_exp_f32_e32 v121, v96
	v_exp_f32_e32 v96, v97
	v_exp_f32_e32 v97, v98
	v_pk_add_f32 v[122:123], v[162:163], v[218:219]
	v_exp_f32_e32 v120, v99
	v_pk_add_f32 v[98:99], v[156:157], v[216:217]
	v_mfma_f32_32x32x16_bf16 v[16:31], v[112:115], v[192:195], v[16:31]
	v_add_f32_e64 v122, v222, v122
	v_add_f32_e64 v123, v223, v123
	v_add_f32_e64 v98, v220, v98
	v_add_f32_e64 v99, v221, v99
	v_exp_f32_e32 v163, v100
	v_exp_f32_e32 v184, v101
	v_exp_f32_e32 v185, v102
	v_exp_f32_e32 v162, v103
	v_pk_add_f32 v[122:123], v[226:227], v[122:123]
	v_pk_add_f32 v[98:99], v[224:225], v[98:99]
	v_pk_add_f32 v[122:123], v[230:231], v[122:123]
	v_pk_add_f32 v[98:99], v[228:229], v[98:99]
	v_pk_add_f32 v[168:169], v[122:123], v[96:97]
	v_pk_add_f32 v[156:157], v[98:99], v[120:121]
	v_cvt_pk_bf16_f32 v96, v121, v96
	v_cvt_pk_bf16_f32 v97, v97, v120
	v_cvt_pk_bf16_f32 v98, v163, v184
	v_cvt_pk_bf16_f32 v99, v185, v162
	s_waitcnt lgkmcnt(0)
	v_mfma_f32_32x32x16_bf16 v[0:15], v[180:183], v[174:177], v[0:15]
	ds_read_b128 v[100:103], v200 offset:28672
	ds_read_b128 v[180:183], v200 offset:32768
	v_exp_f32_e32 v171, v104
	v_exp_f32_e32 v188, v105
	v_exp_f32_e32 v189, v106
	v_exp_f32_e32 v170, v107
	v_exp_f32_e32 v187, v108
	v_exp_f32_e32 v190, v109
	v_mfma_f32_32x32x16_bf16 v[64:79], v[116:119], v[136:139], v[64:79]
	v_exp_f32_e32 v191, v110
	v_exp_f32_e32 v186, v111
	v_cvt_pk_bf16_f32 v104, v171, v188
	v_cvt_pk_bf16_f32 v105, v189, v170
	v_cvt_pk_bf16_f32 v106, v187, v190
	v_cvt_pk_bf16_f32 v107, v191, v186
	v_mfma_f32_32x32x16_bf16 v[16:31], v[124:127], v[174:177], v[16:31]
	s_waitcnt lgkmcnt(0)
	v_mfma_f32_32x32x16_bf16 v[16:31], v[100:103], v[96:99], v[16:31]
	ds_read_b128 v[108:111], v151 offset:28672
	ds_read_b128 v[218:221], v151 offset:32768
	s_waitcnt lgkmcnt(0)
	v_mfma_f32_32x32x16_bf16 v[16:31], v[108:111], v[104:107], v[16:31]
	s_waitcnt vmcnt(2)
	s_mov_b32 m0, s4
	s_waitcnt lgkmcnt(0)
	s_barrier
	s_add_i32 s11, 0, 0x10000
	v_add_u32_e32 v215, s11, v207
	ds_read_b128 v[100:103], v201 offset:61440
	ds_read_b128 v[222:225], v215
	v_mfma_f32_32x32x16_bf16 v[0:15], v[180:183], v[96:99], v[0:15]
	v_add_u32_e32 v216, s11, v208
	ds_read_b128 v[96:99], v202 offset:61440
	ds_read_b128 v[180:183], v216
	v_exp_f32_e32 v226, v80
	v_exp_f32_e32 v227, v81
	v_exp_f32_e32 v228, v82
	v_exp_f32_e32 v229, v83
	v_mfma_f32_32x32x16_bf16 v[32:47], v[144:147], v[192:195], v[32:47]
	v_mfma_f32_32x32x16_bf16 v[0:15], v[218:221], v[104:107], v[0:15]
	s_mov_b32 m0, s4
	s_nop 0
	global_load_lds_dwordx4 v244, s[34:35]
	s_waitcnt lgkmcnt(0)
	v_mfma_f32_32x32x16_bf16 v[112:127], v[100:103], v[132:135], v[48:63]
	ds_read_b128 v[80:83], v204 offset:61440
	v_add_u32_e32 v217, s11, v209
	ds_read_b128 v[192:195], v217
	v_exp_f32_e32 v84, v84
	v_exp_f32_e32 v85, v85
	v_exp_f32_e32 v86, v86
	v_exp_f32_e32 v87, v87
	v_cvt_pk_bf16_f32 v220, v226, v227
	v_mfma_f32_32x32x16_bf16 v[112:127], v[96:99], v[128:131], v[112:127]
	v_cvt_pk_bf16_f32 v221, v228, v229
	v_mfma_f32_32x32x16_bf16 v[96:111], v[222:225], v[132:135], v[48:63]
	v_cvt_pk_bf16_f32 v222, v84, v85
	v_cvt_pk_bf16_f32 v223, v86, v87
	v_mfma_f32_32x32x16_bf16 v[32:47], v[144:147], v[174:177], v[32:47]
	v_add_u32_e32 v218, s11, v210
	v_exp_f32_e32 v88, v88
	v_exp_f32_e32 v89, v89
	v_exp_f32_e32 v90, v90
	v_exp_f32_e32 v91, v91
	s_mov_b32 m0, s5
	s_nop 0
	global_load_lds_dwordx4 v245, s[42:43]
	s_waitcnt lgkmcnt(0)
	v_mfma_f32_32x32x16_bf16 v[112:127], v[80:83], v[140:143], v[112:127]
	ds_read_b128 v[80:83], v203 offset:61440
	ds_read_b128 v[84:87], v218
	s_waitcnt lgkmcnt(0)
	v_mfma_f32_32x32x16_bf16 v[112:127], v[80:83], v[136:139], v[112:127]
	v_exp_f32_e32 v80, v92
	v_exp_f32_e32 v81, v93
	v_exp_f32_e32 v82, v94
	v_exp_f32_e32 v83, v95
	v_cvt_pk_bf16_f32 v174, v88, v89
	v_cvt_pk_bf16_f32 v175, v90, v91
	v_cvt_pk_bf16_f32 v176, v80, v81
	v_mfma_f32_32x32x16_bf16 v[96:111], v[180:183], v[128:131], v[96:111]
	v_cvt_pk_bf16_f32 v177, v82, v83
	ds_read_b128 v[80:83], v206 offset:49152
	ds_read_b128 v[88:91], v206 offset:53248
	v_mfma_f32_32x32x16_bf16 v[96:111], v[192:195], v[140:143], v[96:111]
	s_waitcnt lgkmcnt(0)
	v_mfma_f32_32x32x16_bf16 v[0:15], v[88:91], v[220:223], v[0:15]
	ds_read_b128 v[92:95], v205 offset:49152
	ds_read_b128 v[180:183], v205 offset:53248
	v_exp_f32_e32 v193, v64
	v_exp_f32_e32 v194, v65
	v_exp_f32_e32 v195, v66
	v_exp_f32_e32 v192, v67
	v_exp_f32_e32 v229, v68
	v_exp_f32_e32 v230, v69
	v_mfma_f32_32x32x16_bf16 v[16:31], v[80:83], v[220:223], v[16:31]
	v_exp_f32_e32 v231, v70
	v_exp_f32_e32 v228, v71
	v_cvt_pk_bf16_f32 v64, v193, v194
	v_cvt_pk_bf16_f32 v65, v195, v192
	v_cvt_pk_bf16_f32 v66, v229, v230
	v_cvt_pk_bf16_f32 v67, v231, v228
	s_waitcnt lgkmcnt(0)
	v_mfma_f32_32x32x16_bf16 v[0:15], v[180:183], v[174:177], v[0:15]
	ds_read_b128 v[68:71], v200 offset:49152
	ds_read_b128 v[180:183], v200 offset:53248
	v_exp_f32_e32 v233, v72
	v_exp_f32_e32 v234, v73
	v_exp_f32_e32 v235, v74
	v_exp_f32_e32 v232, v75
	v_exp_f32_e32 v237, v76
	v_exp_f32_e32 v238, v77
	v_mfma_f32_32x32x16_bf16 v[16:31], v[92:95], v[174:177], v[16:31]
	v_exp_f32_e32 v239, v78
	v_exp_f32_e32 v236, v79
	v_cvt_pk_bf16_f32 v72, v233, v234
	v_cvt_pk_bf16_f32 v73, v235, v232
	v_cvt_pk_bf16_f32 v74, v237, v238
	v_cvt_pk_bf16_f32 v75, v239, v236
	v_mfma_f32_32x32x16_bf16 v[96:111], v[84:87], v[136:139], v[96:111]
	s_waitcnt lgkmcnt(0)
	v_mfma_f32_32x32x16_bf16 v[16:31], v[68:71], v[64:67], v[16:31]
	ds_read_b128 v[76:79], v151 offset:49152
	ds_read_b128 v[224:227], v151 offset:53248
	s_waitcnt lgkmcnt(0)
	v_mfma_f32_32x32x16_bf16 v[16:31], v[76:79], v[72:75], v[16:31]
	s_waitcnt vmcnt(2)
	s_mov_b32 m0, s6
	s_waitcnt lgkmcnt(0)
	s_barrier
; template <int TYPE, bool FIXREF>
; DI void attn_dense_unit(const Params& p, int layer, int head, int qb, char* lds, float bref) {
;     ...
;   for (int t = 0; t < NT - 4; t += 4) {
;     STEP(sA0, sA1, sB0, sB1, t, true, true, R0, R1, R3);
;     STEP(sB0, sB1, sA0, sA1, t + 1, true, true, R1, R2, R0);
;     STEP(sA0, sA1, sB0, sB1, t + 2, true, true, R2, R3, R1);
;     STEP(sB0, sB1, sA0, sA1, t + 3, true, true, R3, R0, R2);
;   }
	ds_read_b128 v[68:71], v201
	ds_read_b128 v[164:167], v201 offset:4096
	v_mfma_f32_32x32x16_bf16 v[0:15], v[180:183], v[64:67], v[0:15]
	ds_read_b128 v[64:67], v202
	ds_read_b128 v[180:183], v202 offset:4096
	s_mov_b32 m0, s6
	s_nop 0
	global_load_lds_dwordx4 v244, s[44:45]
	s_waitcnt lgkmcnt(0)
	v_mfma_f32_32x32x16_bf16 v[80:95], v[68:71], v[132:135], v[48:63]
	v_exp_f32_e32 v68, v112
	v_exp_f32_e32 v69, v113
	v_exp_f32_e32 v70, v114
	v_exp_f32_e32 v71, v115
	v_mfma_f32_32x32x16_bf16 v[32:47], v[144:147], v[220:223], v[32:47]
	v_mfma_f32_32x32x16_bf16 v[0:15], v[224:227], v[72:75], v[0:15]
	v_mfma_f32_32x32x16_bf16 v[80:95], v[64:67], v[128:131], v[80:95]
	v_exp_f32_e32 v64, v116
	v_exp_f32_e32 v65, v117
	v_exp_f32_e32 v66, v118
	v_exp_f32_e32 v67, v119
	v_cvt_pk_bf16_f32 v116, v68, v69
	v_cvt_pk_bf16_f32 v117, v70, v71
	v_cvt_pk_bf16_f32 v118, v64, v65
	v_cvt_pk_bf16_f32 v119, v66, v67
	v_mfma_f32_32x32x16_bf16 v[64:79], v[164:167], v[132:135], v[48:63]
	ds_read_b128 v[112:115], v204
	ds_read_b128 v[220:223], v204 offset:4096
	s_mov_b32 m0, s7
	s_nop 0
	global_load_lds_dwordx4 v245, s[46:47]
	s_waitcnt lgkmcnt(0)
	v_mfma_f32_32x32x16_bf16 v[80:95], v[112:115], v[140:143], v[80:95]
	ds_read_b128 v[112:115], v203
	ds_read_b128 v[224:227], v203 offset:4096
	v_exp_f32_e32 v120, v120
	v_exp_f32_e32 v121, v121
	v_exp_f32_e32 v122, v122
	v_exp_f32_e32 v123, v123
	v_mfma_f32_32x32x16_bf16 v[32:47], v[144:147], v[174:177], v[32:47]
	v_mfma_f32_32x32x16_bf16 v[64:79], v[180:183], v[128:131], v[64:79]
	v_add_u32_e32 v166, 0, v211
	v_add_u32_e32 v167, s11, v211
	s_waitcnt lgkmcnt(0)
	v_mfma_f32_32x32x16_bf16 v[80:95], v[112:115], v[136:139], v[80:95]
	v_exp_f32_e32 v114, v124
	v_exp_f32_e32 v115, v125
	v_exp_f32_e32 v124, v126
	v_exp_f32_e32 v125, v127
	v_cvt_pk_bf16_f32 v112, v120, v121
	v_cvt_pk_bf16_f32 v113, v122, v123
	v_cvt_pk_bf16_f32 v114, v114, v115
	v_mfma_f32_32x32x16_bf16 v[64:79], v[220:223], v[140:143], v[64:79]
	v_cvt_pk_bf16_f32 v115, v124, v125
	ds_read_b128 v[120:123], v166 offset:61440
	ds_read_b128 v[124:127], v167
	s_waitcnt lgkmcnt(0)
	v_mfma_f32_32x32x16_bf16 v[0:15], v[124:127], v[116:119], v[0:15]
	v_add_u32_e32 v164, 0, v212
	v_add_u32_e32 v165, s11, v212
	ds_read_b128 v[174:177], v164 offset:61440
	ds_read_b128 v[180:183], v165
	v_exp_f32_e32 v127, v96
	v_exp_f32_e32 v222, v97
	v_exp_f32_e32 v223, v98
	v_mfma_f32_32x32x16_bf16 v[16:31], v[120:123], v[116:119], v[16:31]
	v_exp_f32_e32 v126, v99
	v_exp_f32_e32 v241, v100
	v_exp_f32_e32 v242, v101
	v_exp_f32_e32 v243, v102
	v_exp_f32_e32 v240, v103
	v_cvt_pk_bf16_f32 v96, v127, v222
	v_cvt_pk_bf16_f32 v97, v223, v126
	v_cvt_pk_bf16_f32 v98, v241, v242
	v_cvt_pk_bf16_f32 v99, v243, v240
	v_mfma_f32_32x32x16_bf16 v[32:47], v[144:147], v[116:119], v[32:47]
	v_exp_f32_e32 v125, v104
	v_exp_f32_e32 v104, v105
	v_exp_f32_e32 v105, v106
	v_exp_f32_e32 v124, v107
	v_pk_add_f32 v[106:107], v[162:163], v[156:157]
	v_pk_add_f32 v[168:169], v[184:185], v[168:169]
	v_pk_add_f32 v[106:107], v[170:171], v[106:107]
	v_pk_add_f32 v[168:169], v[188:189], v[168:169]
	v_pk_add_f32 v[106:107], v[186:187], v[106:107]
	v_pk_add_f32 v[168:169], v[190:191], v[168:169]
	v_pk_add_f32 v[106:107], v[106:107], v[192:193]
	s_waitcnt lgkmcnt(0)
	v_mfma_f32_32x32x16_bf16 v[0:15], v[180:183], v[112:115], v[0:15]
	v_add_f32_e64 v168, v168, v194
	v_add_f32_e64 v169, v169, v195
	v_add_f32_e64 v106, v228, v106
	v_add_f32_e64 v107, v229, v107
	v_add_f32_e64 v168, v230, v168
	v_add_f32_e64 v169, v231, v169
	v_pk_add_f32 v[106:107], v[232:233], v[106:107]
	v_pk_add_f32 v[168:169], v[234:235], v[168:169]
	v_pk_add_f32 v[106:107], v[236:237], v[106:107]
	v_add_u32_e32 v219, 0, v213
	v_mfma_f32_32x32x16_bf16 v[64:79], v[224:227], v[136:139], v[64:79]
	v_add_u32_e32 v220, s11, v213
	v_add_f32_e64 v168, v238, v168
	v_add_f32_e64 v169, v239, v169
	v_add_f32_e64 v106, v106, v126
	v_add_f32_e64 v107, v107, v127
	v_exp_f32_e32 v127, v108
	v_exp_f32_e32 v108, v109
	v_exp_f32_e32 v109, v110
	v_exp_f32_e32 v126, v111
	v_mfma_f32_32x32x16_bf16 v[16:31], v[174:177], v[112:115], v[16:31]
	ds_read_b128 v[100:103], v219 offset:61440
	ds_read_b128 v[120:123], v220
	v_add_f32_e64 v168, v168, v222
	v_add_f32_e64 v169, v169, v223
	v_add_f32_e64 v106, v240, v106
	v_add_f32_e64 v107, v241, v107
	v_pk_add_f32 v[168:169], v[242:243], v[168:169]
	v_pk_add_f32 v[106:107], v[124:125], v[106:107]
	v_pk_add_f32 v[168:169], v[104:105], v[168:169]
	v_mfma_f32_32x32x16_bf16 v[32:47], v[144:147], v[112:115], v[32:47]
	v_add_f32_e64 v162, v108, v168
	v_add_f32_e64 v163, v109, v169
	v_add_f32_e64 v156, v126, v106
	v_add_f32_e64 v157, v127, v107
	v_cvt_pk_bf16_f32 v104, v125, v104
	v_cvt_pk_bf16_f32 v105, v105, v124
	v_cvt_pk_bf16_f32 v106, v127, v108
	v_cvt_pk_bf16_f32 v107, v109, v126
	s_waitcnt lgkmcnt(0)
	v_mfma_f32_32x32x16_bf16 v[16:31], v[100:103], v[96:99], v[16:31]
	v_add_u32_e32 v168, 0, v214
	v_add_u32_e32 v169, s11, v214
	ds_read_b128 v[100:103], v168 offset:61440
	ds_read_b128 v[108:111], v169
	v_mfma_f32_32x32x16_bf16 v[0:15], v[120:123], v[96:99], v[0:15]
	s_waitcnt lgkmcnt(0)
	v_mfma_f32_32x32x16_bf16 v[16:31], v[100:103], v[104:107], v[16:31]
	v_mfma_f32_32x32x16_bf16 v[0:15], v[108:111], v[104:107], v[0:15]
	s_waitcnt vmcnt(2)
	s_waitcnt lgkmcnt(0)
	s_barrier
	s_add_u32 s12, s12, s66
	s_addc_u32 s13, s13, s67
	s_add_u32 s16, s16, s66
	s_addc_u32 s17, s17, s67
	s_add_u32 s34, s34, s66
	s_addc_u32 s35, s35, s67
	s_add_u32 s44, s44, s66
	s_addc_u32 s45, s45, s67
	s_add_u32 s14, s14, s64
	s_addc_u32 s15, s15, s65
	s_add_u32 s18, s18, s64
	s_addc_u32 s19, s19, s65
	s_add_u32 s42, s42, s64
	s_addc_u32 s43, s43, s65
	s_add_u32 s46, s46, s64
	s_addc_u32 s47, s47, s65
	s_add_i32 s9, s9, 4
	s_cmpk_lt_u32 s9, 0xf8
	s_cbranch_scc1 .LBB0_541
; template <int TYPE, bool FIXREF>
; DI void attn_dense_unit(const Params& p, int layer, int head, int qb, char* lds, float bref) {
;     ...
;   STEP(sA0, sA1, sB0, sB1, NT - 4, true, true, R0, R1, R3);
;   STEP(sB0, sB1, sA0, sA1, NT - 3, true, false, R1, R2, R0);
	s_mov_b64 s[0:1], 0xef10000
	s_mov_b32 m0, s10
	v_lshl_add_u64 v[96:97], v[154:155], 0, s[0:1]
	s_mov_b64 s[0:1], 0x7f80
	global_load_lds_dwordx4 v[96:97], off
	v_lshl_add_u64 v[96:97], v[152:153], 0, s[0:1]
	s_mov_b32 m0, s8
	s_mov_b64 s[88:89], 0x17618300
	global_load_lds_dwordx4 v[96:97], off
	ds_read_b128 v[96:99], v201 offset:20480
	ds_read_b128 v[144:147], v201 offset:24576
	s_mov_b64 s[62:63], 0x33ba200
	ds_read_b128 v[100:103], v202 offset:20480
	ds_read_b128 v[152:155], v202 offset:24576
	v_exp_f32_e32 v170, v80
	v_exp_f32_e32 v171, v81
	v_exp_f32_e32 v172, v82
	v_exp_f32_e32 v175, v83
	s_waitcnt lgkmcnt(0)
	v_mfma_f32_32x32x16_bf16 v[112:127], v[96:99], v[132:135], v[48:63]
	ds_read_b128 v[80:83], v204 offset:20480
	ds_read_b128 v[158:161], v204 offset:24576
	v_exp_f32_e32 v84, v84
	v_exp_f32_e32 v85, v85
	v_exp_f32_e32 v86, v86
	v_exp_f32_e32 v87, v87
	v_mfma_f32_32x32x16_bf16 v[112:127], v[100:103], v[128:131], v[112:127]
	v_cvt_pk_bf16_f32 v174, v170, v171
	v_cvt_pk_bf16_f32 v175, v172, v175
	v_cvt_pk_bf16_f32 v176, v84, v85
	v_cvt_pk_bf16_f32 v177, v86, v87
	v_mfma_f32_32x32x16_bf16 v[96:111], v[144:147], v[132:135], v[48:63]
	ds_read_b128 v[84:87], v203 offset:20480
	ds_read_b128 v[144:147], v203 offset:24576
	s_waitcnt lgkmcnt(0)
	v_mfma_f32_32x32x16_bf16 v[112:127], v[80:83], v[140:143], v[112:127]
	v_exp_f32_e32 v80, v88
	v_exp_f32_e32 v81, v89
	v_exp_f32_e32 v82, v90
	v_exp_f32_e32 v83, v91
	v_mfma_f32_32x32x16_bf16 v[112:127], v[84:87], v[136:139], v[112:127]
	v_exp_f32_e32 v84, v92
	v_exp_f32_e32 v85, v93
	v_exp_f32_e32 v86, v94
	v_exp_f32_e32 v87, v95
	v_cvt_pk_bf16_f32 v180, v80, v81
	v_cvt_pk_bf16_f32 v181, v82, v83
	v_cvt_pk_bf16_f32 v182, v84, v85
	v_mfma_f32_32x32x16_bf16 v[96:111], v[152:155], v[128:131], v[96:111]
	v_cvt_pk_bf16_f32 v183, v86, v87
	ds_read_b128 v[80:83], v206 offset:8192
	ds_read_b128 v[84:87], v206 offset:12288
	v_mfma_f32_32x32x16_bf16 v[96:111], v[158:161], v[140:143], v[96:111]
	s_waitcnt lgkmcnt(0)
	v_mfma_f32_32x32x16_bf16 v[0:15], v[84:87], v[174:177], v[0:15]
	ds_read_b128 v[88:91], v205 offset:8192
	ds_read_b128 v[92:95], v205 offset:12288
	v_exp_f32_e32 v153, v64
	v_exp_f32_e32 v171, v65
	v_exp_f32_e32 v184, v66
	v_exp_f32_e32 v152, v67
	v_exp_f32_e32 v170, v68
	v_exp_f32_e32 v172, v69
	v_exp_f32_e32 v186, v70
	v_exp_f32_e32 v154, v71
	v_mfma_f32_32x32x16_bf16 v[16:31], v[80:83], v[174:177], v[16:31]
	v_cvt_pk_bf16_f32 v64, v153, v171
	v_cvt_pk_bf16_f32 v65, v184, v152
	v_cvt_pk_bf16_f32 v66, v170, v172
	v_cvt_pk_bf16_f32 v67, v186, v154
	s_waitcnt lgkmcnt(0)
	v_mfma_f32_32x32x16_bf16 v[0:15], v[92:95], v[180:183], v[0:15]
	ds_read_b128 v[68:71], v200 offset:8192
	ds_read_b128 v[190:193], v200 offset:12288
	v_exp_f32_e32 v185, v72
	v_exp_f32_e32 v187, v73
	v_exp_f32_e32 v189, v74
	v_exp_f32_e32 v158, v75
	v_exp_f32_e32 v155, v76
	v_exp_f32_e32 v188, v77
	v_exp_f32_e32 v194, v78
	v_exp_f32_e32 v160, v79
	v_mfma_f32_32x32x16_bf16 v[96:111], v[144:147], v[136:139], v[96:111]
	v_cvt_pk_bf16_f32 v72, v185, v187
	v_cvt_pk_bf16_f32 v73, v189, v158
	v_cvt_pk_bf16_f32 v74, v155, v188
	v_cvt_pk_bf16_f32 v75, v194, v160
	v_mfma_f32_32x32x16_bf16 v[16:31], v[88:91], v[180:183], v[16:31]
	ds_read_b128 v[76:79], v151 offset:8192
	ds_read_b128 v[208:211], v151 offset:12288
	s_waitcnt lgkmcnt(0)
	v_mfma_f32_32x32x16_bf16 v[16:31], v[68:71], v[64:67], v[16:31]
	v_mfma_f32_32x32x16_bf16 v[16:31], v[76:79], v[72:75], v[16:31]
	s_waitcnt vmcnt(2)
	s_waitcnt lgkmcnt(0)
	s_barrier
	ds_read_b128 v[68:71], v201 offset:40960
	ds_read_b128 v[222:225], v201 offset:45056
	v_mfma_f32_32x32x16_bf16 v[0:15], v[190:193], v[64:67], v[0:15]
	v_mov_b64_e32 v[146:147], s[38:39]
	v_mov_b64_e32 v[144:145], s[36:37]
	v_exp_f32_e32 v159, v112
	v_exp_f32_e32 v161, v113
	v_exp_f32_e32 v195, v114
	v_exp_f32_e32 v207, v115
	v_mfma_f32_32x32x16_bf16 v[0:15], v[208:211], v[72:75], v[0:15]
	v_mfma_f32_32x32x16_bf16 v[32:47], v[144:147], v[174:177], v[32:47]
	ds_read_b128 v[64:67], v202 offset:40960
	ds_read_b128 v[174:177], v202 offset:45056
	s_waitcnt lgkmcnt(0)
	v_mfma_f32_32x32x16_bf16 v[80:95], v[68:71], v[132:135], v[48:63]
	ds_read_b128 v[112:115], v204 offset:40960
	ds_read_b128 v[190:193], v204 offset:45056
	v_exp_f32_e32 v116, v116
	v_exp_f32_e32 v117, v117
	v_exp_f32_e32 v118, v118
	v_exp_f32_e32 v119, v119
	v_mfma_f32_32x32x16_bf16 v[80:95], v[64:67], v[128:131], v[80:95]
	v_cvt_pk_bf16_f32 v208, v159, v161
	v_cvt_pk_bf16_f32 v209, v195, v207
	v_cvt_pk_bf16_f32 v210, v116, v117
	v_cvt_pk_bf16_f32 v211, v118, v119
	v_mfma_f32_32x32x16_bf16 v[64:79], v[222:225], v[132:135], v[48:63]
	s_waitcnt lgkmcnt(0)
	v_mfma_f32_32x32x16_bf16 v[80:95], v[112:115], v[140:143], v[80:95]
	ds_read_b128 v[112:115], v203 offset:40960
	ds_read_b128 v[222:225], v203 offset:45056
	v_exp_f32_e32 v116, v120
	v_exp_f32_e32 v117, v121
	v_exp_f32_e32 v118, v122
	v_exp_f32_e32 v119, v123
	v_mfma_f32_32x32x16_bf16 v[32:47], v[144:147], v[180:183], v[32:47]
	s_waitcnt lgkmcnt(0)
	v_mfma_f32_32x32x16_bf16 v[80:95], v[112:115], v[136:139], v[80:95]
	v_exp_f32_e32 v114, v126
	v_exp_f32_e32 v115, v127
	v_exp_f32_e32 v112, v124
	v_exp_f32_e32 v113, v125
	v_cvt_pk_bf16_f32 v120, v116, v117
	v_cvt_pk_bf16_f32 v123, v114, v115
	ds_read_b128 v[114:117], v206 offset:28672
	ds_read_b128 v[124:127], v206 offset:32768
	v_mfma_f32_32x32x16_bf16 v[64:79], v[174:177], v[128:131], v[64:79]
	v_cvt_pk_bf16_f32 v121, v118, v119
	v_cvt_pk_bf16_f32 v122, v112, v113
	v_mfma_f32_32x32x16_bf16 v[64:79], v[190:193], v[140:143], v[64:79]
	s_waitcnt lgkmcnt(0)
; template <int TYPE, bool FIXREF>
; DI void attn_dense_unit(const Params& p, int layer, int head, int qb, char* lds, float bref) {
;     ...
;   STEP(sB0, sB1, sA0, sA1, NT - 3, true, false, R1, R2, R0);
;   STEP(sA0, sA1, sB0, sB1, NT - 2, true, false, R2, R3, R1);
	v_mfma_f32_32x32x16_bf16 v[0:15], v[124:127], v[208:211], v[0:15]
	ds_read_b128 v[174:177], v205 offset:28672
	ds_read_b128 v[180:183], v205 offset:32768
	v_exp_f32_e32 v159, v96
	v_exp_f32_e32 v195, v97
	v_exp_f32_e32 v207, v98
	v_exp_f32_e32 v112, v99
	v_exp_f32_e32 v161, v100
	v_exp_f32_e32 v221, v101
	v_mfma_f32_32x32x16_bf16 v[16:31], v[114:117], v[208:211], v[16:31]
	v_exp_f32_e32 v226, v102
	v_exp_f32_e32 v114, v103
	v_cvt_pk_bf16_f32 v124, v159, v195
	v_cvt_pk_bf16_f32 v125, v207, v112
	v_cvt_pk_bf16_f32 v126, v161, v221
	v_cvt_pk_bf16_f32 v127, v226, v114
	s_waitcnt lgkmcnt(0)
	v_mfma_f32_32x32x16_bf16 v[0:15], v[180:183], v[120:123], v[0:15]
	ds_read_b128 v[96:99], v200 offset:28672
	ds_read_b128 v[180:183], v200 offset:32768
	v_exp_f32_e32 v113, v104
	v_exp_f32_e32 v227, v105
	v_exp_f32_e32 v228, v106
	v_exp_f32_e32 v116, v107
	v_exp_f32_e32 v115, v108
	v_exp_f32_e32 v229, v109
	v_exp_f32_e32 v230, v110
	v_exp_f32_e32 v118, v111
	v_mfma_f32_32x32x16_bf16 v[64:79], v[222:225], v[136:139], v[64:79]
	v_cvt_pk_bf16_f32 v190, v113, v227
	v_cvt_pk_bf16_f32 v191, v228, v116
	v_cvt_pk_bf16_f32 v192, v115, v229
	v_cvt_pk_bf16_f32 v193, v230, v118
	v_mfma_f32_32x32x16_bf16 v[16:31], v[174:177], v[120:123], v[16:31]
	ds_read_b128 v[100:103], v151 offset:28672
	ds_read_b128 v[174:177], v151 offset:32768
	s_waitcnt lgkmcnt(0)
	v_mfma_f32_32x32x16_bf16 v[16:31], v[96:99], v[124:127], v[16:31]
	v_mfma_f32_32x32x16_bf16 v[16:31], v[100:103], v[190:193], v[16:31]
	s_waitcnt vmcnt(0)
	s_waitcnt lgkmcnt(0)
	s_barrier
	ds_read_b128 v[222:225], v201 offset:61440
	ds_read_b128 v[212:215], v215
	v_mfma_f32_32x32x16_bf16 v[0:15], v[180:183], v[124:127], v[0:15]
	ds_read_b128 v[124:127], v202 offset:61440
	ds_read_b128 v[180:183], v216
	v_exp_f32_e32 v117, v80
	v_exp_f32_e32 v119, v81
	v_exp_f32_e32 v201, v82
	v_exp_f32_e32 v202, v83
	v_mfma_f32_32x32x16_bf16 v[0:15], v[174:177], v[190:193], v[0:15]
	s_waitcnt lgkmcnt(0)
	v_mfma_f32_32x32x16_bf16 v[96:111], v[222:225], v[132:135], v[48:63]
	v_mfma_f32_32x32x16_bf16 v[32:47], v[144:147], v[208:211], v[32:47]
	ds_read_b128 v[80:83], v204 offset:61440
	ds_read_b128 v[174:177], v217
	v_mfma_f32_32x32x16_bf16 v[96:111], v[124:127], v[128:131], v[96:111]
	v_exp_f32_e32 v124, v84
	v_exp_f32_e32 v125, v85
	v_exp_f32_e32 v126, v86
	v_exp_f32_e32 v87, v87
	v_cvt_pk_bf16_f32 v84, v117, v119
	v_cvt_pk_bf16_f32 v85, v201, v202
	v_cvt_pk_bf16_f32 v86, v124, v125
	v_cvt_pk_bf16_f32 v87, v126, v87
	v_mfma_f32_32x32x16_bf16 v[48:63], v[212:215], v[132:135], v[48:63]
	s_waitcnt lgkmcnt(0)
	v_mfma_f32_32x32x16_bf16 v[96:111], v[80:83], v[140:143], v[96:111]
	ds_read_b128 v[80:83], v203 offset:61440
	ds_read_b128 v[124:127], v218
	v_exp_f32_e32 v88, v88
	v_exp_f32_e32 v89, v89
	v_exp_f32_e32 v90, v90
	v_exp_f32_e32 v91, v91
	v_mfma_f32_32x32x16_bf16 v[32:47], v[144:147], v[120:123], v[32:47]
	s_waitcnt lgkmcnt(0)
	v_mfma_f32_32x32x16_bf16 v[96:111], v[80:83], v[136:139], v[96:111]
	v_exp_f32_e32 v82, v92
	v_exp_f32_e32 v83, v93
	v_exp_f32_e32 v92, v94
	v_exp_f32_e32 v93, v95
	v_cvt_pk_bf16_f32 v80, v88, v89
	v_cvt_pk_bf16_f32 v81, v90, v91
	v_cvt_pk_bf16_f32 v82, v82, v83
	v_mfma_f32_32x32x16_bf16 v[48:63], v[180:183], v[128:131], v[48:63]
	v_cvt_pk_bf16_f32 v83, v92, v93
	ds_read_b128 v[88:91], v206 offset:49152
	ds_read_b128 v[92:95], v206 offset:53248
	v_mfma_f32_32x32x16_bf16 v[48:63], v[174:177], v[140:143], v[48:63]
	s_waitcnt lgkmcnt(0)
	v_mfma_f32_32x32x16_bf16 v[0:15], v[92:95], v[84:87], v[0:15]
	ds_read_b128 v[120:123], v205 offset:49152
	ds_read_b128 v[128:131], v205 offset:53248
	v_exp_f32_e32 v117, v64
	v_exp_f32_e32 v132, v65
	v_exp_f32_e32 v133, v66
	v_exp_f32_e32 v64, v67
	v_exp_f32_e32 v119, v68
	v_exp_f32_e32 v134, v69
	v_exp_f32_e32 v135, v70
	v_exp_f32_e32 v66, v71
	v_mfma_f32_32x32x16_bf16 v[16:31], v[88:91], v[84:87], v[16:31]
	v_cvt_pk_bf16_f32 v88, v117, v132
	v_cvt_pk_bf16_f32 v89, v133, v64
	v_cvt_pk_bf16_f32 v90, v119, v134
	v_cvt_pk_bf16_f32 v91, v135, v66
	s_waitcnt lgkmcnt(0)
	v_mfma_f32_32x32x16_bf16 v[0:15], v[128:131], v[80:83], v[0:15]
	ds_read_b128 v[92:95], v200 offset:49152
	ds_read_b128 v[128:131], v200 offset:53248
	v_exp_f32_e32 v65, v72
	v_exp_f32_e32 v140, v73
	v_exp_f32_e32 v141, v74
	v_exp_f32_e32 v68, v75
	v_exp_f32_e32 v67, v76
	v_exp_f32_e32 v70, v79
	v_mfma_f32_32x32x16_bf16 v[48:63], v[124:127], v[136:139], v[48:63]
	v_exp_f32_e32 v124, v77
	v_exp_f32_e32 v125, v78
	v_cvt_pk_bf16_f32 v72, v65, v140
	v_cvt_pk_bf16_f32 v73, v141, v68
	v_cvt_pk_bf16_f32 v74, v67, v124
	v_cvt_pk_bf16_f32 v75, v125, v70
	v_mfma_f32_32x32x16_bf16 v[16:31], v[120:123], v[80:83], v[16:31]
	ds_read_b128 v[76:79], v151 offset:49152
	ds_read_b128 v[120:123], v151 offset:53248
	s_waitcnt lgkmcnt(0)
	v_mfma_f32_32x32x16_bf16 v[16:31], v[92:95], v[88:91], v[16:31]
	v_mfma_f32_32x32x16_bf16 v[16:31], v[76:79], v[72:75], v[16:31]
	s_waitcnt vmcnt(0)
	s_waitcnt lgkmcnt(0)
	s_barrier
; template <int TYPE, bool FIXREF>
; DI void attn_dense_unit(const Params& p, int layer, int head, int qb, char* lds, float bref) {
;     ...
;   STEP(sB0, sB1, sA0, sA1, NT - 1, false, false, R3, R0, R2);
;   lsum += ls0 + ls1 + ls2;
	v_mfma_f32_32x32x16_bf16 v[0:15], v[128:131], v[88:91], v[0:15]
	v_exp_f32_e32 v69, v96
	v_exp_f32_e32 v71, v97
	v_exp_f32_e32 v77, v98
	v_exp_f32_e32 v78, v99
	v_mfma_f32_32x32x16_bf16 v[32:47], v[144:147], v[84:87], v[32:47]
	v_exp_f32_e32 v79, v100
	v_exp_f32_e32 v84, v101
	v_exp_f32_e32 v85, v102
	v_exp_f32_e32 v86, v103
	v_mfma_f32_32x32x16_bf16 v[32:47], v[144:147], v[80:83], v[32:47]
	v_cvt_pk_bf16_f32 v76, v69, v71
	v_cvt_pk_bf16_f32 v77, v77, v78
	v_cvt_pk_bf16_f32 v78, v79, v84
	v_cvt_pk_bf16_f32 v79, v85, v86
	v_exp_f32_e32 v69, v104
	v_exp_f32_e32 v71, v105
	v_exp_f32_e32 v80, v106
	v_exp_f32_e32 v81, v107
	v_exp_f32_e32 v82, v108
	v_exp_f32_e32 v83, v109
	v_exp_f32_e32 v84, v110
	v_exp_f32_e32 v85, v111
	v_mfma_f32_32x32x16_bf16 v[0:15], v[120:123], v[72:75], v[0:15]
	v_cvt_pk_bf16_f32 v73, v80, v81
	v_cvt_pk_bf16_f32 v74, v82, v83
	v_cvt_pk_bf16_f32 v75, v84, v85
	ds_read_b128 v[80:83], v166 offset:61440
	ds_read_b128 v[84:87], v167
	v_cvt_pk_bf16_f32 v72, v69, v71
	s_waitcnt lgkmcnt(0)
	v_mfma_f32_32x32x16_bf16 v[0:15], v[84:87], v[76:79], v[0:15]
	ds_read_b128 v[84:87], v164 offset:61440
	ds_read_b128 v[88:91], v165
	v_mfma_f32_32x32x16_bf16 v[16:31], v[80:83], v[76:79], v[16:31]
	v_exp_f32_e32 v69, v48
	v_add_f32_e32 v48, v163, v184
	v_add_f32_e32 v48, v186, v48
	v_add_f32_e32 v48, v189, v48
	v_add_f32_e32 v48, v194, v48
	v_add_f32_e32 v48, v48, v207
	v_add_f32_e32 v48, v226, v48
	v_add_f32_e32 v48, v228, v48
	v_add_f32_e32 v48, v230, v48
	s_waitcnt lgkmcnt(0)
	v_mfma_f32_32x32x16_bf16 v[0:15], v[88:91], v[72:75], v[0:15]
	v_exp_f32_e32 v88, v59
	v_exp_f32_e32 v59, v50
	v_add_f32_e32 v48, v48, v133
	v_exp_f32_e32 v71, v52
	v_exp_f32_e32 v52, v53
	v_exp_f32_e32 v53, v54
	v_add_f32_e32 v48, v135, v48
	v_mfma_f32_32x32x16_bf16 v[16:31], v[84:87], v[72:75], v[16:31]
	v_exp_f32_e32 v85, v56
	v_exp_f32_e32 v56, v58
	v_add_f32_e32 v48, v141, v48
	v_exp_f32_e32 v58, v62
	v_add_f32_e32 v48, v125, v48
	v_add_f32_e32 v48, v48, v59
	v_add_f32_e32 v48, v53, v48
	v_add_f32_e32 v48, v56, v48
	v_add_f32_e32 v91, v58, v48
	v_add_f32_e32 v48, v162, v171
	v_add_f32_e32 v48, v172, v48
	v_add_f32_e32 v48, v187, v48
	v_add_f32_e32 v48, v188, v48
	v_add_f32_e32 v48, v48, v195
	v_add_f32_e32 v48, v221, v48
	v_add_f32_e32 v48, v227, v48
	v_add_f32_e32 v48, v229, v48
	v_exp_f32_e32 v86, v55
	v_exp_f32_e32 v55, v49
	v_add_f32_e32 v48, v48, v132
	v_add_f32_e32 v48, v134, v48
	v_exp_f32_e32 v54, v57
	v_add_f32_e32 v48, v140, v48
	v_exp_f32_e32 v57, v61
	v_add_f32_e32 v48, v124, v48
	v_mfma_f32_32x32x16_bf16 v[32:47], v[144:147], v[76:79], v[32:47]
	v_add_f32_e32 v48, v48, v55
	v_add_f32_e32 v48, v52, v48
	v_add_f32_e32 v48, v54, v48
	ds_read_b128 v[80:83], v219 offset:61440
	ds_read_b128 v[92:95], v220
	v_add_f32_e32 v89, v57, v48
	v_add_f32_e32 v48, v157, v153
	v_exp_f32_e32 v84, v51
	v_exp_f32_e32 v90, v63
	v_exp_f32_e32 v87, v60
	v_add_f32_e32 v153, v170, v48
	v_mov_b32_e32 v157, v185
	v_pk_add_f32 v[48:49], v[156:157], v[152:153]
	v_mfma_f32_32x32x16_bf16 v[32:47], v[144:147], v[72:75], v[32:47]
	v_add_f32_e64 v48, v154, v48
	v_add_f32_e64 v49, v155, v49
	v_add_f32_e64 v48, v158, v48
	v_add_f32_e64 v49, v159, v49
	v_add_f32_e64 v50, v160, v48
	v_add_f32_e64 v51, v161, v49
	s_nop 5
	v_cvt_pk_bf16_f32 v34, v69, v55
	v_cvt_pk_bf16_f32 v35, v59, v84
	v_cvt_pk_bf16_f32 v36, v71, v52
	v_cvt_pk_bf16_f32 v37, v53, v86
	v_cvt_pk_bf16_f32 v38, v85, v54
	v_cvt_pk_bf16_f32 v39, v56, v88
	v_cvt_pk_bf16_f32 v40, v87, v57
	v_cvt_pk_bf16_f32 v41, v58, v90
	s_waitcnt lgkmcnt(0)
	v_mfma_f32_32x32x16_bf16 v[0:15], v[92:95], v[34:37], v[0:15]
	ds_read_b128 v[42:45], v168 offset:61440
	ds_read_b128 v[46:49], v169
	v_mfma_f32_32x32x16_bf16 v[16:31], v[80:83], v[34:37], v[16:31]
	s_waitcnt lgkmcnt(0)
	v_mfma_f32_32x32x16_bf16 v[0:15], v[46:49], v[38:41], v[0:15]
	v_mfma_f32_32x32x16_bf16 v[16:31], v[42:45], v[38:41], v[16:31]
	v_add_f32_e64 v34, v50, v112
	v_add_f32_e64 v35, v51, v113
	v_lshlrev_b32_e32 v172, 1, v150
	v_add_f32_e64 v34, v114, v34
	v_add_f32_e64 v35, v115, v35
	s_waitcnt vmcnt(0)
	s_waitcnt lgkmcnt(0)
	s_barrier
; DI unsigned pk2(float lo, float hi) { f32x2 v = {lo, hi}; bf16x2_t b = __builtin_convertvector(v, bf16x2_t); return __builtin_bit_cast(unsigned, b); }
; DI void store_o_wide(bf16_t* rowp, const f32x16& o, float inv, int h) {
; #pragma unroll
;   for (int pr = 0; pr < 2; ++pr) {
;     const int g = 2 * pr;
;     const unsigned ax = pk2(o[4 * g] * inv, o[4 * g + 1] * inv), ay = pk2(o[4 * g + 2] * inv, o[4 * g + 3] * inv);
;     const unsigned bx = pk2(o[4 * g + 4] * inv, o[4 * g + 5] * inv), by = pk2(o[4 * g + 6] * inv, o[4 * g + 7] * inv);
;     const auto sx = __builtin_amdgcn_permlane32_swap(ax, bx, false, false);
;     const auto sy = __builtin_amdgcn_permlane32_swap(ay, by, false, false);
;     const u32x4 w = {sx[0], sy[0], sx[1], sy[1]};
;     *(u32x4*)(rowp + 8 * (g + h)) = w;
;   }
; }
; template <int TYPE, bool FIXREF>
; DI void attn_dense_unit(const Params& p, int layer, int head, int qb, char* lds, float bref) {
;     ...
;   lsum += ls0 + ls1 + ls2;
;   const float l = (NONES > 0 ? la[0] : 0.f) + lsum + __shfl_xor(lsum, 32);
;     ...
;   const float inv = 1.0f / l;
;   bf16_t* op = O + (size_t)q * 512 + head * 64;
;   store_o_wide(op, o0, inv, h); store_o_wide(op + 32, o1, inv, h);
	v_pk_add_f32 v[34:35], v[116:117], v[34:35]
	s_nop 0
	v_pk_add_f32 v[34:35], v[118:119], v[34:35]
	s_nop 0
	v_pk_add_f32 v[34:35], v[34:35], v[64:65]
	s_nop 0
	v_pk_add_f32 v[34:35], v[66:67], v[34:35]
	s_nop 0
	v_pk_add_f32 v[34:35], v[68:69], v[34:35]
	s_nop 0
	v_pk_add_f32 v[34:35], v[70:71], v[34:35]
	s_nop 0
	v_pk_add_f32 v[34:35], v[34:35], v[84:85]
	s_nop 0
	v_pk_add_f32 v[34:35], v[86:87], v[34:35]
	s_nop 0
	v_pk_add_f32 v[34:35], v[88:89], v[34:35]
	s_nop 0
	v_pk_add_f32 v[34:35], v[90:91], v[34:35]
	s_nop 0
	v_add_f32_e32 v33, v34, v35
	ds_bpermute_b32 v34, v199, v33
	v_add_f32_e32 v32, v33, v32
	s_waitcnt lgkmcnt(0)
	v_add_f32_e32 v32, v32, v34
	v_div_scale_f32 v33, s[0:1], v32, v32, 1.0
	v_rcp_f32_e32 v34, v33
	v_readlane_b32 s0, v253, 13
	v_readlane_b32 s1, v253, 14
	v_fma_f32 v35, -v33, v34, 1.0
	v_fmac_f32_e32 v34, v35, v34
	v_div_scale_f32 v35, vcc, 1.0, v32, 1.0
	v_mul_f32_e32 v36, v35, v34
	v_fma_f32 v37, -v33, v36, v35
	v_fmac_f32_e32 v36, v37, v34
	v_fma_f32 v33, -v33, v36, v35
	v_div_fmas_f32 v33, v33, v34, v36
	v_div_fixup_f32 v32, v33, v32, 1.0
	v_lshlrev_b64 v[34:35], 10, v[148:149]
	v_pk_mul_f32 v[16:17], v[16:17], v[32:33] op_sel_hi:[1,0]
	v_pk_mul_f32 v[18:19], v[18:19], v[32:33] op_sel_hi:[1,0]
	v_pk_mul_f32 v[0:1], v[0:1], v[32:33] op_sel_hi:[1,0]
	v_pk_mul_f32 v[2:3], v[2:3], v[32:33] op_sel_hi:[1,0]
	v_lshl_add_u64 v[34:35], s[0:1], 0, v[34:35]
	v_cvt_pk_bf16_f32 v16, v16, v17
	v_cvt_pk_bf16_f32 v17, v18, v19
	v_pk_mul_f32 v[18:19], v[20:21], v[32:33] op_sel_hi:[1,0]
	v_pk_mul_f32 v[20:21], v[22:23], v[32:33] op_sel_hi:[1,0]
	v_cvt_pk_bf16_f32 v0, v0, v1
	v_cvt_pk_bf16_f32 v1, v2, v3
	v_pk_mul_f32 v[2:3], v[4:5], v[32:33] op_sel_hi:[1,0]
	v_pk_mul_f32 v[4:5], v[6:7], v[32:33] op_sel_hi:[1,0]
	v_lshl_add_u64 v[34:35], v[34:35], 0, s[68:69]
	v_cvt_pk_bf16_f32 v18, v18, v19
	v_cvt_pk_bf16_f32 v19, v20, v21
	v_cvt_pk_bf16_f32 v2, v2, v3
	v_cvt_pk_bf16_f32 v3, v4, v5
	v_permlane32_swap_b32_e32 v16, v18
	v_permlane32_swap_b32_e32 v17, v19
	v_lshl_add_u64 v[20:21], v[34:35], 0, v[172:173]
	v_permlane32_swap_b32_e32 v0, v2
	v_permlane32_swap_b32_e32 v1, v3
	global_store_dwordx4 v[20:21], v[16:19], off
	global_store_dwordx4 v[20:21], v[0:3], off offset:64
	v_pk_mul_f32 v[22:23], v[30:31], v[32:33] op_sel_hi:[1,0]
	v_pk_mul_f32 v[16:17], v[24:25], v[32:33] op_sel_hi:[1,0]
	v_pk_mul_f32 v[18:19], v[26:27], v[32:33] op_sel_hi:[1,0]
	v_pk_mul_f32 v[0:1], v[8:9], v[32:33] op_sel_hi:[1,0]
	v_pk_mul_f32 v[2:3], v[10:11], v[32:33] op_sel_hi:[1,0]
	v_cvt_pk_bf16_f32 v16, v16, v17
	v_cvt_pk_bf16_f32 v17, v18, v19
	v_pk_mul_f32 v[18:19], v[28:29], v[32:33] op_sel_hi:[1,0]
	v_cvt_pk_bf16_f32 v0, v0, v1
	v_cvt_pk_bf16_f32 v1, v2, v3
	v_pk_mul_f32 v[2:3], v[12:13], v[32:33] op_sel_hi:[1,0]
	v_pk_mul_f32 v[6:7], v[14:15], v[32:33] op_sel_hi:[1,0]
	v_cvt_pk_bf16_f32 v18, v18, v19
	v_cvt_pk_bf16_f32 v19, v22, v23
	v_cvt_pk_bf16_f32 v2, v2, v3
	v_cvt_pk_bf16_f32 v3, v6, v7
	v_permlane32_swap_b32_e32 v16, v18
	v_permlane32_swap_b32_e32 v17, v19
	v_lshl_add_u64 v[4:5], v[20:21], 0, 64
	v_permlane32_swap_b32_e32 v0, v2
	v_permlane32_swap_b32_e32 v1, v3
	global_store_dwordx4 v[20:21], v[16:19], off offset:32
